# proj GEMM mixer epilogue: conv weights prefetched before the K-loop into a freed constant register and broadcast with DPP row_newbcast; no vmcnt wait in that epilogue
# baseline (speedup 1.0000x reference)
; #define LAS __attribute__((address_space(3)))
; #define OPQV(x) asm volatile("" : "+v"(x))
; DEV void sgu_item(LAS unsigned char* lds, const bf16_t* P, const bf16_t* VN, const float* sgu_w, const float* sgu_b, bf16_t* OC, int item) {
;     int tid = threadIdx.x; OPQV(tid); const int lane = tid & 63, wv = tid >> 6, fr = lane & 15, g4 = lane >> 4;
;     LAS bf16_t* VT = (LAS bf16_t*)lds;
;     const int g = item & 7, ch = (item >> 3) & 15, b = item >> 7;
;     const size_t tok0 = (size_t)b * S_ + ch * 128;
;     const int t = wv * 16 + fr;
;     const size_t tok = tok0 + t;
;     u32x4 vin[4];
; #pragma unroll
;     for (int it = 0; it < 4; ++it) { const int idx = it * 512 + tid, s = idx >> 4, c8 = (idx & 15) * 8; vin[it] = *(const u32x4*)(VN + (tok0 + s) * 1024 + g * 128 + c8); }
;     const float* wrow = sgu_w + ((size_t)g * 128 + t) * 128;
;     f32x4 wa[4], wb[4];
; #pragma unroll
;     for (int ks = 0; ks < 4; ++ks) { wa[ks] = *(const f32x4*)(wrow + ks * 32 + g4 * 8); wb[ks] = *(const f32x4*)(wrow + ks * 32 + g4 * 8 + 4); }
;     u32x2 uu[8];
; #pragma unroll
;     for (int n = 0; n < 8; ++n) uu[n] = *(const u32x2*)(P + tok * NP + COL_U + g * 128 + n * 16 + g4 * 4);
;     const float bias = sgu_b[g * 128 + t];
; #pragma unroll
;     for (int it = 0; it < 4; ++it) { const int idx = it * 512 + tid, s = idx >> 4, c8 = (idx & 15) * 8;
; #pragma unroll
;         for (int j = 0; j < 4; ++j) { VT[(c8 + 2 * j) * 136 + s] = (bf16_t)(vin[it][j] & 0xffffu); VT[(c8 + 2 * j + 1) * 136 + s] = (bf16_t)(vin[it][j] >> 16); } }
;     __syncthreads();
; DEV void phase_mix(LAS unsigned char* lds, const bf16_t* P, const bf16_t* QB, const bf16_t* KV, const bf16_t* KC, const bf16_t* VC, const float* rel_bias, bf16_t* OB,
;                    const bf16_t* VN, const float* sgu_w, const float* sgu_b, bf16_t* OC, int* ctr) {
;     ...
;     for (;;) {
;         if (tid == 0) *(LAS int*)(lds + AT_NEXT) = atomicAdd(ctr, 1);
;         __syncthreads();
;         const int i = *(const LAS int*)(lds + AT_NEXT);
;         __syncthreads();
;         if (i >= 2048) break;
;         if (i < 1024) attn_item(lds, P, QB, KV, KC, VC, rel_bias, OB, (i & 31) >> 2, i & 3, 31 - (i >> 5));
;         else sgu_item(lds, P, VN, sgu_w, sgu_b, OC, i - 1024);
.LBB0_164:
	s_or_b64 exec, exec, s[4:5]
	v_mov_b32_e32 v0, s95
	s_waitcnt lgkmcnt(0)
	s_barrier
	ds_read_b32 v0, v0
	s_movk_i32 s4, 0x7ff
	s_waitcnt lgkmcnt(0)
	s_barrier
	v_cmp_lt_i32_e32 vcc, s4, v0
	v_readfirstlane_b32 s43, v0
	s_mov_b64 s[4:5], -1
	s_cbranch_vccnz .LBB0_159
	s_cmpk_gt_i32 s43, 0x3ff
	s_cbranch_scc0 .LBB0_167
	s_add_i32 s4, s43, 0xfffffc00
	s_lshl_b32 s5, s4, 4
	s_lshl_b32 s4, s4, 7
	v_mov_b32_e32 v8, v210
	s_and_b32 s6, s4, 0x380
	s_and_b32 s36, s5, 0x3f80
	v_lshlrev_b32_e32 v0, 3, v8
	s_lshl_b32 s4, s6, 1
	v_and_b32_e32 v9, 0x78, v0
	s_add_u32 s44, s34, s4
	v_ashrrev_i32_e32 v4, 4, v8
	s_addc_u32 s45, s35, 0
	v_lshlrev_b32_e32 v0, 1, v9
	v_ashrrev_i32_e32 v5, 31, v4
	v_lshl_add_u64 v[2:3], s[44:45], 0, v[0:1]
	v_lshl_add_u64 v[6:7], v[4:5], 0, s[36:37]
	v_add_u32_e32 v0, 0x200, v8
	v_lshlrev_b64 v[6:7], 11, v[6:7]
	v_ashrrev_i32_e32 v70, 4, v0
	v_lshl_add_u64 v[6:7], v[2:3], 0, v[6:7]
	v_ashrrev_i32_e32 v71, 31, v70
	global_load_dwordx4 v[30:33], v[6:7], off
	v_lshl_add_u64 v[6:7], v[70:71], 0, s[36:37]
	v_add_u32_e32 v0, 0x400, v8
	v_lshlrev_b64 v[6:7], 11, v[6:7]
	v_ashrrev_i32_e32 v72, 4, v0
	v_lshl_add_u64 v[6:7], v[2:3], 0, v[6:7]
	v_ashrrev_i32_e32 v73, 31, v72
	global_load_dwordx4 v[34:37], v[6:7], off
	v_lshl_add_u64 v[6:7], v[72:73], 0, s[36:37]
	v_add_u32_e32 v0, 0x600, v8
	v_lshlrev_b64 v[6:7], 11, v[6:7]
	v_ashrrev_i32_e32 v74, 4, v0
	v_lshl_add_u64 v[6:7], v[2:3], 0, v[6:7]
	v_ashrrev_i32_e32 v75, 31, v74
	global_load_dwordx4 v[38:41], v[6:7], off
	v_lshl_add_u64 v[6:7], v[74:75], 0, s[36:37]
	v_ashrrev_i32_e32 v0, 2, v8
	v_lshlrev_b64 v[6:7], 11, v[6:7]
	s_waitcnt vmcnt(11)
	v_bfi_b32 v28, -16, v0, v8
	v_lshl_add_u64 v[2:3], v[2:3], 0, v[6:7]
	v_ashrrev_i32_e32 v29, 31, v28
	s_mov_b32 s7, s37
	global_load_dwordx4 v[42:45], v[2:3], off
	v_lshl_add_u64 v[2:3], v[28:29], 0, s[6:7]
	v_bfe_u32 v0, v8, 4, 2
	v_lshlrev_b64 v[2:3], 9, v[2:3]
	v_lshl_add_u64 v[2:3], s[80:81], 0, v[2:3]
	v_lshlrev_b32_e32 v6, 5, v0
	v_mov_b32_e32 v7, v1
	v_lshl_add_u64 v[6:7], v[2:3], 0, v[6:7]
	global_load_dwordx4 v[46:49], v[6:7], off
	global_load_dwordx4 v[50:53], v[6:7], off offset:16
	v_mov_b64_e32 v[2:3], s[76:77]
	v_and_b32_e32 v82, 15, v8
	v_add_u32_e32 v8, s6, v28
	s_movk_i32 s6, 0x110
	v_lshl_add_u64 v[24:25], v[28:29], 0, s[36:37]
	s_mov_b32 s5, s37
	v_mad_u32_u24 v71, v9, s6, 0
	v_ashrrev_i32_e32 v9, 31, v8
	v_mad_i64_i32 v[2:3], s[6:7], v24, s59, v[2:3]
	v_lshl_add_u32 v73, v4, 1, v71
	v_lshlrev_b32_e32 v0, 3, v0
	v_lshl_add_u64 v[4:5], v[8:9], 2, s[82:83]
	v_lshl_add_u64 v[2:3], v[2:3], 0, s[4:5]
	global_load_dword v29, v[4:5], off
	v_lshl_add_u64 v[10:11], v[2:3], 0, v[0:1]
	global_load_dwordx4 v[54:57], v[6:7], off offset:144
	global_load_dwordx4 v[58:61], v[6:7], off offset:128
	global_load_dwordx4 v[62:65], v[6:7], off offset:272
	global_load_dwordx4 v[66:69], v[6:7], off offset:256
	global_load_dwordx4 v[2:5], v[6:7], off offset:400
	s_nop 0
	global_load_dwordx4 v[6:9], v[6:7], off offset:384
	s_mov_b64 s[6:7], 0x2c00
	s_movk_i32 s5, 0x2000
	v_lshl_add_u64 v[76:77], v[10:11], 0, s[6:7]
	v_add_co_u32_e32 v10, vcc, s5, v10
	v_or_b32_e32 v90, 32, v0
	s_nop 0
	v_addc_co_u32_e32 v11, vcc, 0, v11, vcc
	global_load_dwordx2 v[22:23], v[76:77], off offset:32
	global_load_dwordx2 v[20:21], v[76:77], off offset:64
	global_load_dwordx2 v[18:19], v[76:77], off offset:96
	global_load_dwordx2 v[16:17], v[76:77], off offset:128
	global_load_dwordx2 v[26:27], v[10:11], off offset:3072
	global_load_dwordx2 v[14:15], v[76:77], off offset:160
	global_load_dwordx2 v[12:13], v[76:77], off offset:192
	s_nop 0
	global_load_dwordx2 v[10:11], v[76:77], off offset:224
	v_cmp_le_i32_e32 vcc, v0, v28
	v_or_b32_e32 v91, 33, v0
	s_movk_i32 s5, 0x88
	v_mad_u32_u24 v83, v82, s5, v227
	v_mov_b32_e32 v252, 0x1100
	v_mad_u32_u24 v84, v82, s5, v252
	v_mad_u32_u24 v85, v82, s5, v216
	v_mad_u32_u24 v86, v82, s5, v217
	v_mad_u32_u24 v87, v82, s5, v218
	s_waitcnt vmcnt(20)
	ds_write_b16 v73, v30
	ds_write_b16_d16_hi v73, v30 offset:272
	ds_write_b16 v73, v31 offset:544
	ds_write_b16_d16_hi v73, v31 offset:816
	ds_write_b16 v73, v32 offset:1088
	ds_write_b16_d16_hi v73, v32 offset:1360
	ds_write_b16 v73, v33 offset:1632
	ds_write_b16_d16_hi v73, v33 offset:1904
	v_lshl_add_u32 v30, v70, 1, v71
	s_waitcnt vmcnt(19)
	ds_write_b16 v30, v34
	ds_write_b16_d16_hi v30, v34 offset:272
	ds_write_b16 v30, v35 offset:544
	ds_write_b16_d16_hi v30, v35 offset:816
	ds_write_b16 v30, v36 offset:1088
	ds_write_b16_d16_hi v30, v36 offset:1360
	ds_write_b16 v30, v37 offset:1632
	ds_write_b16_d16_hi v30, v37 offset:1904
	v_lshl_add_u32 v30, v72, 1, v71
	s_waitcnt vmcnt(18)
	ds_write_b16 v30, v38
	ds_write_b16_d16_hi v30, v38 offset:272
	ds_write_b16 v30, v39 offset:544
	ds_write_b16_d16_hi v30, v39 offset:816
	ds_write_b16 v30, v40 offset:1088
	ds_write_b16_d16_hi v30, v40 offset:1360
	ds_write_b16 v30, v41 offset:1632
	ds_write_b16_d16_hi v30, v41 offset:1904
	v_lshl_add_u32 v30, v74, 1, v71
	s_waitcnt vmcnt(17)
	ds_write_b16 v30, v42
	ds_write_b16_d16_hi v30, v42 offset:272
	ds_write_b16 v30, v43 offset:544
	ds_write_b16_d16_hi v30, v43 offset:816
	ds_write_b16 v30, v44 offset:1088
	ds_write_b16_d16_hi v30, v44 offset:1360
	ds_write_b16 v30, v45 offset:1632
	ds_write_b16_d16_hi v30, v45 offset:1904
	v_or_b32_e32 v32, 2, v0
	v_or_b32_e32 v33, 3, v0
	v_or_b32_e32 v34, 4, v0
	v_or_b32_e32 v35, 5, v0
	v_or_b32_e32 v36, 6, v0
	v_or_b32_e32 v37, 7, v0
	s_waitcnt vmcnt(16) lgkmcnt(0)
	v_cndmask_b32_e32 v30, 0, v46, vcc
	v_cmp_lt_i32_e32 vcc, v0, v28
	s_barrier
; #define LAS __attribute__((address_space(3)))
; DEV u32x4 pack8(const float (&f)[8]) { u32x4 w; w.x = cvt_pk_bf16(f[0], f[1]); w.y = cvt_pk_bf16(f[2], f[3]); w.z = cvt_pk_bf16(f[4], f[5]); w.w = cvt_pk_bf16(f[6], f[7]); return w; }
; DEV void sgu_item(LAS unsigned char* lds, const bf16_t* P, const bf16_t* VN, const float* sgu_w, const float* sgu_b, bf16_t* OC, int item) {
;     ...
; #pragma unroll
;     for (int ks = 0; ks < 4; ++ks) { const int s0 = ks * 32 + g4 * 8;
;         float wf[8] = {wa[ks][0], wa[ks][1], wa[ks][2], wa[ks][3], wb[ks][0], wb[ks][1], wb[ks][2], wb[ks][3]};
; #pragma unroll
;         for (int j = 0; j < 8; ++j) if (s0 + j > t) wf[j] = 0.f;
;         const bf16x8 wfr = as_bf16x8(pack8(wf));
; #pragma unroll
;         for (int n = 0; n < 8; ++n) { const bf16x8 vf = *(const LAS bf16x8*)(lds + ((n * 16 + fr) * 136 + s0) * 2);
;             acc[n] = __builtin_amdgcn_mfma_f32_16x16x32_bf16(vf, wfr, acc[n], 0, 0, 0); } }
	s_nop 0
	v_cndmask_b32_e32 v31, 0, v47, vcc
	v_cmp_le_i32_e32 vcc, v32, v28
	v_cvt_pk_bf16_f32 v30, v30, v31
	v_mad_u32_u24 v88, v82, s5, v219
	v_mad_u32_u24 v89, v82, s5, v220
	v_cndmask_b32_e32 v32, 0, v48, vcc
	v_cmp_le_i32_e32 vcc, v33, v28
	v_add_u32_e32 v38, v83, v0
	v_add_u32_e32 v42, v84, v0
	v_cndmask_b32_e32 v33, 0, v49, vcc
	v_cmp_le_i32_e32 vcc, v34, v28
	v_cvt_pk_bf16_f32 v31, v32, v33
	v_add_u32_e32 v46, v85, v0
	v_add_u32_e32 v70, v87, v0
	s_waitcnt vmcnt(15)
	v_cndmask_b32_e32 v34, 0, v50, vcc
	v_cmp_le_i32_e32 vcc, v35, v28
	v_add_u32_e32 v50, v86, v0
	v_add_u32_e32 v74, v88, v0
	v_cndmask_b32_e32 v35, 0, v51, vcc
	v_cmp_le_i32_e32 vcc, v36, v28
	v_cvt_pk_bf16_f32 v32, v34, v35
	v_mad_u32_u24 v34, v82, s5, v0
	v_lshl_add_u32 v34, v34, 1, 0
	v_cndmask_b32_e32 v36, 0, v52, vcc
	v_cmp_le_i32_e32 vcc, v37, v28
	v_add_u32_e32 v78, v89, v0
	v_lshl_add_u32 v38, v38, 1, 0
	v_cndmask_b32_e32 v37, 0, v53, vcc
	v_cmp_le_i32_e32 vcc, v90, v28
	v_cvt_pk_bf16_f32 v33, v36, v37
	ds_read_b128 v[34:37], v34
	ds_read_b128 v[38:41], v38
	s_waitcnt vmcnt(12)
	v_cndmask_b32_e32 v58, 0, v58, vcc
	v_cmp_le_i32_e32 vcc, v91, v28
	v_or_b32_e32 v91, 34, v0
	v_lshl_add_u32 v42, v42, 1, 0
	v_cndmask_b32_e32 v59, 0, v59, vcc
	v_cmp_le_i32_e32 vcc, v91, v28
	v_or_b32_e32 v91, 35, v0
	v_lshl_add_u32 v46, v46, 1, 0
	v_cndmask_b32_e32 v60, 0, v60, vcc
	v_cmp_le_i32_e32 vcc, v91, v28
	v_or_b32_e32 v91, 36, v0
	v_lshl_add_u32 v50, v50, 1, 0
	v_cndmask_b32_e32 v61, 0, v61, vcc
	v_cmp_le_i32_e32 vcc, v91, v28
	v_lshl_add_u32 v70, v70, 1, 0
	v_lshl_add_u32 v74, v74, 1, 0
	v_cndmask_b32_e32 v91, 0, v54, vcc
	v_or_b32_e32 v54, 37, v0
	v_cmp_le_i32_e32 vcc, v54, v28
	v_or_b32_e32 v54, 38, v0
	v_lshl_add_u32 v78, v78, 1, 0
	v_cndmask_b32_e32 v92, 0, v55, vcc
	v_cmp_le_i32_e32 vcc, v54, v28
	v_or_b32_e32 v54, 39, v0
	ds_read_b128 v[42:45], v42
	ds_read_b128 v[46:49], v46
	ds_read_b128 v[50:53], v50
	ds_read_b128 v[70:73], v70
	ds_read_b128 v[74:77], v74
	ds_read_b128 v[78:81], v78
	v_cndmask_b32_e32 v93, 0, v56, vcc
	v_cmp_le_i32_e32 vcc, v54, v28
	v_cvt_pk_bf16_f32 v54, v58, v59
	v_mad_u32_u24 v58, v82, s5, v90
	v_lshl_add_u32 v58, v58, 1, 0
	v_cndmask_b32_e32 v57, 0, v57, vcc
	v_cvt_pk_bf16_f32 v55, v60, v61
	v_cvt_pk_bf16_f32 v56, v91, v92
	v_cvt_pk_bf16_f32 v57, v93, v57
	ds_read_b128 v[58:61], v58
	s_waitcnt lgkmcnt(8)
	v_mfma_f32_16x16x32_bf16 v[34:37], v[34:37], v[30:33], 0
	v_lshlrev_b64 v[24:25], 11, v[24:25]
	v_lshl_add_u64 v[24:25], s[88:89], 0, v[24:25]
	s_waitcnt lgkmcnt(7)
	v_mfma_f32_16x16x32_bf16 v[38:41], v[38:41], v[30:33], 0
	s_waitcnt lgkmcnt(6)
	v_mfma_f32_16x16x32_bf16 v[42:45], v[42:45], v[30:33], 0
	s_waitcnt lgkmcnt(5)
	v_mfma_f32_16x16x32_bf16 v[46:49], v[46:49], v[30:33], 0
	s_waitcnt lgkmcnt(4)
	v_mfma_f32_16x16x32_bf16 v[50:53], v[50:53], v[30:33], 0
	s_waitcnt lgkmcnt(3)
	v_mfma_f32_16x16x32_bf16 v[70:73], v[70:73], v[30:33], 0
	s_waitcnt lgkmcnt(2)
	v_mfma_f32_16x16x32_bf16 v[74:77], v[74:77], v[30:33], 0
	s_waitcnt lgkmcnt(1)
	v_mfma_f32_16x16x32_bf16 v[30:33], v[78:81], v[30:33], 0
	v_add_u32_e32 v78, v90, v83
	v_lshl_add_u32 v78, v78, 1, 0
	ds_read_b128 v[78:81], v78
	s_waitcnt lgkmcnt(1)
	v_mfma_f32_16x16x32_bf16 v[34:37], v[58:61], v[54:57], v[34:37]
	v_add_u32_e32 v58, v90, v84
	v_lshl_add_u32 v58, v58, 1, 0
	ds_read_b128 v[58:61], v58
	s_waitcnt lgkmcnt(1)
	v_mfma_f32_16x16x32_bf16 v[38:41], v[78:81], v[54:57], v[38:41]
	v_add_u32_e32 v78, v90, v85
	v_lshl_add_u32 v78, v78, 1, 0
	ds_read_b128 v[78:81], v78
	s_waitcnt lgkmcnt(1)
	v_mfma_f32_16x16x32_bf16 v[42:45], v[58:61], v[54:57], v[42:45]
	v_add_u32_e32 v58, v90, v86
	v_lshl_add_u32 v58, v58, 1, 0
	ds_read_b128 v[58:61], v58
	s_waitcnt lgkmcnt(1)
	v_mfma_f32_16x16x32_bf16 v[46:49], v[78:81], v[54:57], v[46:49]
	v_add_u32_e32 v78, v90, v87
	v_lshl_add_u32 v78, v78, 1, 0
	ds_read_b128 v[78:81], v78
	s_waitcnt lgkmcnt(1)
	v_mfma_f32_16x16x32_bf16 v[50:53], v[58:61], v[54:57], v[50:53]
	v_add_u32_e32 v58, v90, v88
	v_lshl_add_u32 v58, v58, 1, 0
	ds_read_b128 v[58:61], v58
	s_waitcnt lgkmcnt(1)
	v_mfma_f32_16x16x32_bf16 v[70:73], v[78:81], v[54:57], v[70:73]
	v_add_u32_e32 v78, v90, v89
	v_lshl_add_u32 v78, v78, 1, 0
	ds_read_b128 v[78:81], v78
	s_waitcnt lgkmcnt(1)
	v_mfma_f32_16x16x32_bf16 v[58:61], v[58:61], v[54:57], v[74:77]
	s_nop 2
	v_or_b32_e32 v74, 64, v0
	v_cmp_le_i32_e32 vcc, v74, v28
	v_or_b32_e32 v75, 0x41, v0
	s_waitcnt lgkmcnt(0)
	v_mfma_f32_16x16x32_bf16 v[30:33], v[78:81], v[54:57], v[30:33]
	s_waitcnt vmcnt(10)
	v_cndmask_b32_e32 v66, 0, v66, vcc
	v_cmp_le_i32_e32 vcc, v75, v28
	v_or_b32_e32 v75, 0x42, v0
	v_add_u32_e32 v54, v74, v83
	v_cndmask_b32_e32 v67, 0, v67, vcc
	v_cmp_le_i32_e32 vcc, v75, v28
	v_or_b32_e32 v75, 0x43, v0
	v_lshl_add_u32 v54, v54, 1, 0
	v_cndmask_b32_e32 v68, 0, v68, vcc
	v_cmp_le_i32_e32 vcc, v75, v28
	v_or_b32_e32 v75, 0x44, v0
	s_nop 0
	v_cndmask_b32_e32 v69, 0, v69, vcc
	v_cmp_le_i32_e32 vcc, v75, v28
	s_nop 1
	v_cndmask_b32_e32 v75, 0, v62, vcc
	v_or_b32_e32 v62, 0x45, v0
	v_cmp_le_i32_e32 vcc, v62, v28
	v_or_b32_e32 v62, 0x46, v0
	s_nop 0
	v_cndmask_b32_e32 v76, 0, v63, vcc
	v_cmp_le_i32_e32 vcc, v62, v28
	v_or_b32_e32 v62, 0x47, v0
	s_nop 0
	v_cndmask_b32_e32 v77, 0, v64, vcc
	v_cmp_le_i32_e32 vcc, v62, v28
	v_cvt_pk_bf16_f32 v62, v66, v67
	v_mad_u32_u24 v66, v82, s5, v74
	v_lshl_add_u32 v66, v66, 1, 0
	v_cndmask_b32_e32 v65, 0, v65, vcc
	v_cvt_pk_bf16_f32 v63, v68, v69
	v_cvt_pk_bf16_f32 v64, v75, v76
	v_cvt_pk_bf16_f32 v65, v77, v65
	ds_read_b128 v[66:69], v66
	ds_read_b128 v[54:57], v54
	s_waitcnt lgkmcnt(1)
	v_mfma_f32_16x16x32_bf16 v[34:37], v[66:69], v[62:65], v[34:37]
	v_add_u32_e32 v66, v74, v84
	v_lshl_add_u32 v66, v66, 1, 0
	ds_read_b128 v[66:69], v66
	s_waitcnt lgkmcnt(1)
; #define LAS __attribute__((address_space(3)))
; DEV u32x4 pack8(const float (&f)[8]) { u32x4 w; w.x = cvt_pk_bf16(f[0], f[1]); w.y = cvt_pk_bf16(f[2], f[3]); w.z = cvt_pk_bf16(f[4], f[5]); w.w = cvt_pk_bf16(f[6], f[7]); return w; }
; DEV void sgu_item(LAS unsigned char* lds, const bf16_t* P, const bf16_t* VN, const float* sgu_w, const float* sgu_b, bf16_t* OC, int item) {
;     ...
;     for (int ks = 0; ks < 4; ++ks) { const int s0 = ks * 32 + g4 * 8;
;         float wf[8] = {wa[ks][0], wa[ks][1], wa[ks][2], wa[ks][3], wb[ks][0], wb[ks][1], wb[ks][2], wb[ks][3]};
; #pragma unroll
;         for (int j = 0; j < 8; ++j) if (s0 + j > t) wf[j] = 0.f;
;         const bf16x8 wfr = as_bf16x8(pack8(wf));
; #pragma unroll
;         for (int n = 0; n < 8; ++n) { const bf16x8 vf = *(const LAS bf16x8*)(lds + ((n * 16 + fr) * 136 + s0) * 2);
;             acc[n] = __builtin_amdgcn_mfma_f32_16x16x32_bf16(vf, wfr, acc[n], 0, 0, 0); } }
	v_mfma_f32_16x16x32_bf16 v[38:41], v[54:57], v[62:65], v[38:41]
	v_add_u32_e32 v54, v74, v85
	v_lshl_add_u32 v54, v54, 1, 0
	ds_read_b128 v[54:57], v54
	s_waitcnt lgkmcnt(1)
	v_mfma_f32_16x16x32_bf16 v[42:45], v[66:69], v[62:65], v[42:45]
	v_add_u32_e32 v66, v74, v86
	v_lshl_add_u32 v66, v66, 1, 0
	ds_read_b128 v[66:69], v66
	s_waitcnt lgkmcnt(1)
	v_mfma_f32_16x16x32_bf16 v[46:49], v[54:57], v[62:65], v[46:49]
	v_add_u32_e32 v54, v74, v87
	v_lshl_add_u32 v54, v54, 1, 0
	ds_read_b128 v[54:57], v54
	s_waitcnt lgkmcnt(1)
	v_mfma_f32_16x16x32_bf16 v[50:53], v[66:69], v[62:65], v[50:53]
	v_add_u32_e32 v66, v74, v88
	v_lshl_add_u32 v66, v66, 1, 0
	ds_read_b128 v[66:69], v66
	s_waitcnt lgkmcnt(1)
	v_mfma_f32_16x16x32_bf16 v[54:57], v[54:57], v[62:65], v[70:73]
	s_nop 2
	v_add_u32_e32 v70, v74, v89
	v_lshl_add_u32 v70, v70, 1, 0
	ds_read_b128 v[70:73], v70
	s_waitcnt lgkmcnt(1)
	v_mfma_f32_16x16x32_bf16 v[58:61], v[66:69], v[62:65], v[58:61]
	v_or_b32_e32 v66, 0x60, v0
	v_cmp_le_i32_e32 vcc, v66, v28
	v_or_b32_e32 v67, 0x61, v0
	s_waitcnt lgkmcnt(0)
	v_mfma_f32_16x16x32_bf16 v[30:33], v[70:73], v[62:65], v[30:33]
	s_waitcnt vmcnt(8)
	v_cndmask_b32_e32 v6, 0, v6, vcc
	v_cmp_le_i32_e32 vcc, v67, v28
	v_or_b32_e32 v67, 0x62, v0
	s_nop 0
	v_cndmask_b32_e32 v7, 0, v7, vcc
	v_cmp_le_i32_e32 vcc, v67, v28
	v_or_b32_e32 v67, 0x63, v0
	s_nop 0
	v_cndmask_b32_e32 v8, 0, v8, vcc
	v_cmp_le_i32_e32 vcc, v67, v28
	v_or_b32_e32 v67, 0x64, v0
	s_nop 0
	v_cndmask_b32_e32 v9, 0, v9, vcc
	v_cmp_le_i32_e32 vcc, v67, v28
	s_nop 1
	v_cndmask_b32_e32 v67, 0, v2, vcc
	v_or_b32_e32 v2, 0x65, v0
	v_cmp_le_i32_e32 vcc, v2, v28
	v_or_b32_e32 v2, 0x66, v0
	s_nop 0
	v_cndmask_b32_e32 v68, 0, v3, vcc
	v_cmp_le_i32_e32 vcc, v2, v28
	v_or_b32_e32 v2, 0x67, v0
	v_or_b32_e32 v0, s4, v0
	v_cndmask_b32_e32 v69, 0, v4, vcc
	v_cmp_le_i32_e32 vcc, v2, v28
	v_cvt_pk_bf16_f32 v2, v6, v7
	v_mad_u32_u24 v6, v82, s5, v66
	v_lshl_add_u32 v6, v6, 1, 0
	v_cndmask_b32_e32 v5, 0, v5, vcc
	v_cvt_pk_bf16_f32 v3, v8, v9
	v_cvt_pk_bf16_f32 v4, v67, v68
	v_cvt_pk_bf16_f32 v5, v69, v5
	ds_read_b128 v[6:9], v6
	v_add_u32_e32 v28, v66, v83
	v_lshl_add_u32 v28, v28, 1, 0
	ds_read_b128 v[62:65], v28
	v_add_u32_e32 v28, v66, v84
	v_lshl_add_u32 v28, v28, 1, 0
	s_waitcnt lgkmcnt(1)
	v_mfma_f32_16x16x32_bf16 v[6:9], v[6:9], v[2:5], v[34:37]
	s_nop 2
	ds_read_b128 v[34:37], v28
	v_add_u32_e32 v28, v66, v85
	v_lshl_add_u32 v28, v28, 1, 0
	s_waitcnt lgkmcnt(1)
	v_mfma_f32_16x16x32_bf16 v[38:41], v[62:65], v[2:5], v[38:41]
	ds_read_b128 v[62:65], v28
	v_add_u32_e32 v28, v66, v86
	v_lshl_add_u32 v28, v28, 1, 0
	s_waitcnt lgkmcnt(1)
	v_mfma_f32_16x16x32_bf16 v[34:37], v[34:37], v[2:5], v[42:45]
	v_add_f32_e32 v6, v29, v6
	s_nop 1
	ds_read_b128 v[42:45], v28
	v_add_u32_e32 v28, v66, v87
	v_lshl_add_u32 v28, v28, 1, 0
	s_waitcnt lgkmcnt(1)
	v_mfma_f32_16x16x32_bf16 v[46:49], v[62:65], v[2:5], v[46:49]
	ds_read_b128 v[62:65], v28
	v_add_u32_e32 v28, v66, v88
	v_lshl_add_u32 v28, v28, 1, 0
	s_waitcnt lgkmcnt(1)
	v_mfma_f32_16x16x32_bf16 v[42:45], v[42:45], v[2:5], v[50:53]
	v_add_f32_e32 v7, v29, v7
	s_nop 1
	ds_read_b128 v[50:53], v28
	v_add_u32_e32 v28, v66, v89
	v_lshl_add_u32 v28, v28, 1, 0
	s_waitcnt lgkmcnt(1)
	v_mfma_f32_16x16x32_bf16 v[54:57], v[62:65], v[2:5], v[54:57]
	ds_read_b128 v[62:65], v28
	s_waitcnt vmcnt(3)
; DEV float bflo(unsigned u) { return __uint_as_float(u << 16); }
; DEV float bfhi(unsigned u) { return __uint_as_float(u & 0xffff0000u); }
; DEV unsigned cvt_pk_bf16(float lo, float hi) { unsigned r; asm volatile("v_cvt_pk_bf16_f32 %0, %1, %2" : "=v"(r) : "v"(lo), "v"(hi)); return r; }
; DEV void sgu_item(LAS unsigned char* lds, const bf16_t* P, const bf16_t* VN, const float* sgu_w, const float* sgu_b, bf16_t* OC, int item) {
;     ...
; #pragma unroll
;     for (int n = 0; n < 8; ++n) { const int c = g * 128 + n * 16 + g4 * 4;
;         u32x2 w; w.x = cvt_pk_bf16(bflo(uu[n].x) * (acc[n][0] + bias), bfhi(uu[n].x) * (acc[n][1] + bias)); w.y = cvt_pk_bf16(bflo(uu[n].y) * (acc[n][2] + bias), bfhi(uu[n].y) * (acc[n][3] + bias));
;         *(u32x2*)(OC + tok * 1024 + c) = w; }
;     __syncthreads();
	v_lshlrev_b32_e32 v28, 16, v26
	v_and_b32_e32 v26, 0xffff0000, v26
	v_mul_f32_e32 v6, v6, v28
	v_mul_f32_e32 v7, v7, v26
	v_cvt_pk_bf16_f32 v104, v6, v7
	v_lshlrev_b32_e32 v7, 16, v27
	v_add_f32_e32 v8, v29, v8
	v_mul_f32_e32 v7, v8, v7
	v_and_b32_e32 v8, 0xffff0000, v27
	v_add_f32_e32 v9, v29, v9
	v_mul_f32_e32 v8, v9, v8
	v_cvt_pk_bf16_f32 v105, v7, v8
	v_lshl_add_u64 v[8:9], v[24:25], 0, v[0:1]
	v_and_b32_e32 v120, 16, v213
	v_lshrrev_b32_e32 v121, 1, v120
	v_add_u32_e32 v120, v120, v121
	v_add_co_u32_e32 v8, vcc, v8, v120
	s_nop 1
	v_addc_co_u32_e32 v9, vcc, 0, v9, vcc
	v_lshlrev_b32_e32 v0, 16, v22
	v_add_f32_e32 v6, v29, v38
	v_mul_f32_e32 v0, v6, v0
	v_and_b32_e32 v6, 0xffff0000, v22
	v_add_f32_e32 v7, v29, v39
	v_mul_f32_e32 v6, v7, v6
	v_cvt_pk_bf16_f32 v106, v0, v6
	v_lshlrev_b32_e32 v0, 16, v23
	v_add_f32_e32 v7, v29, v40
	v_mul_f32_e32 v0, v7, v0
	v_and_b32_e32 v7, 0xffff0000, v23
	v_add_f32_e32 v22, v29, v41
	v_mul_f32_e32 v7, v22, v7
	v_cvt_pk_bf16_f32 v107, v0, v7
	s_nop 1
	v_permlane16_swap_b32_e32 v104, v106
	v_permlane16_swap_b32_e32 v105, v107
	global_store_dwordx4 v[8:9], v[104:107], off
	v_lshlrev_b32_e32 v0, 16, v20
	v_add_f32_e32 v6, v29, v34
	v_mul_f32_e32 v0, v6, v0
	v_and_b32_e32 v6, 0xffff0000, v20
	v_add_f32_e32 v7, v29, v35
	v_mul_f32_e32 v6, v7, v6
	v_cvt_pk_bf16_f32 v108, v0, v6
	v_lshlrev_b32_e32 v0, 16, v21
	v_add_f32_e32 v7, v29, v36
	v_mul_f32_e32 v0, v7, v0
	v_and_b32_e32 v7, 0xffff0000, v21
	v_add_f32_e32 v20, v29, v37
	v_mul_f32_e32 v7, v20, v7
	v_cvt_pk_bf16_f32 v109, v0, v7
	v_lshlrev_b32_e32 v0, 16, v18
	v_add_f32_e32 v6, v29, v46
	v_mul_f32_e32 v0, v6, v0
	v_and_b32_e32 v6, 0xffff0000, v18
	v_add_f32_e32 v7, v29, v47
	v_mul_f32_e32 v6, v7, v6
	v_cvt_pk_bf16_f32 v110, v0, v6
	v_lshlrev_b32_e32 v0, 16, v19
	v_add_f32_e32 v7, v29, v48
	v_mul_f32_e32 v0, v7, v0
	v_and_b32_e32 v7, 0xffff0000, v19
	v_add_f32_e32 v18, v29, v49
	v_mul_f32_e32 v7, v18, v7
	v_cvt_pk_bf16_f32 v111, v0, v7
	s_nop 1
	v_permlane16_swap_b32_e32 v108, v110
	v_permlane16_swap_b32_e32 v109, v111
	global_store_dwordx4 v[8:9], v[108:111], off offset:64
	v_lshlrev_b32_e32 v0, 16, v16
	v_add_f32_e32 v6, v29, v42
	v_mul_f32_e32 v0, v6, v0
	v_and_b32_e32 v6, 0xffff0000, v16
	v_add_f32_e32 v7, v29, v43
	v_mul_f32_e32 v6, v7, v6
	v_cvt_pk_bf16_f32 v112, v0, v6
	v_lshlrev_b32_e32 v0, 16, v17
	v_add_f32_e32 v7, v29, v44
	v_mul_f32_e32 v0, v7, v0
	v_and_b32_e32 v7, 0xffff0000, v17
	v_add_f32_e32 v16, v29, v45
	v_mul_f32_e32 v7, v16, v7
	v_cvt_pk_bf16_f32 v113, v0, v7
	s_waitcnt vmcnt(4)
	v_lshlrev_b32_e32 v0, 16, v14
	v_add_f32_e32 v6, v29, v54
	v_mul_f32_e32 v0, v6, v0
	v_and_b32_e32 v6, 0xffff0000, v14
	v_add_f32_e32 v7, v29, v55
	s_waitcnt lgkmcnt(1)
	v_mfma_f32_16x16x32_bf16 v[50:53], v[50:53], v[2:5], v[58:61]
	v_mul_f32_e32 v6, v7, v6
	v_cvt_pk_bf16_f32 v114, v0, v6
	v_lshlrev_b32_e32 v0, 16, v15
	v_add_f32_e32 v7, v29, v56
	v_mul_f32_e32 v0, v7, v0
	v_and_b32_e32 v7, 0xffff0000, v15
	v_add_f32_e32 v14, v29, v57
	v_mul_f32_e32 v7, v14, v7
	v_cvt_pk_bf16_f32 v115, v0, v7
	s_nop 1
	v_permlane16_swap_b32_e32 v112, v114
	v_permlane16_swap_b32_e32 v113, v115
	global_store_dwordx4 v[8:9], v[112:115], off offset:128
	s_waitcnt vmcnt(4)
	v_lshlrev_b32_e32 v0, 16, v12
	v_add_f32_e32 v6, v29, v50
	v_mul_f32_e32 v0, v6, v0
	v_and_b32_e32 v6, 0xffff0000, v12
	v_add_f32_e32 v7, v29, v51
	s_waitcnt lgkmcnt(0)
	v_mfma_f32_16x16x32_bf16 v[2:5], v[62:65], v[2:5], v[30:33]
	v_mul_f32_e32 v6, v7, v6
	v_cvt_pk_bf16_f32 v116, v0, v6
	v_lshlrev_b32_e32 v0, 16, v13
	v_add_f32_e32 v7, v29, v52
	v_mul_f32_e32 v0, v7, v0
	v_and_b32_e32 v7, 0xffff0000, v13
	v_add_f32_e32 v12, v29, v53
	v_mul_f32_e32 v7, v12, v7
	v_cvt_pk_bf16_f32 v117, v0, v7
	s_waitcnt vmcnt(3)
	v_lshlrev_b32_e32 v0, 16, v10
	v_add_f32_e32 v2, v29, v2
	v_mul_f32_e32 v0, v2, v0
	v_and_b32_e32 v2, 0xffff0000, v10
	v_add_f32_e32 v3, v29, v3
	v_mul_f32_e32 v2, v3, v2
	v_cvt_pk_bf16_f32 v118, v0, v2
	v_lshlrev_b32_e32 v0, 16, v11
	v_add_f32_e32 v3, v29, v4
	v_mul_f32_e32 v0, v3, v0
	v_and_b32_e32 v3, 0xffff0000, v11
	v_add_f32_e32 v4, v29, v5
	v_mul_f32_e32 v3, v4, v3
	v_cvt_pk_bf16_f32 v119, v0, v3
	s_nop 1
	v_permlane16_swap_b32_e32 v116, v118
	v_permlane16_swap_b32_e32 v117, v119
	global_store_dwordx4 v[8:9], v[116:119], off offset:192
	s_barrier
	s_mov_b64 s[4:5], 0

;     DEV bool next(int i, Unit& u) const { return tile((long)i * G + c, u); }
;     DEV bool next(int i, Unit& u) const { const int round = i / 3, br = i - round * 3; Unit t; if (!so.tile((long)round * so.G + so.c, t)) return false; u.pm = br * 64 + t.pm; u.pn = br * 4 + t.pn; return true; }
;     DEV bool operator()(f32x4 (&acc)[2][2][4][2], const Unit& u, int wr, int wc, int fr, int fq) const {
;     ...
;             const int ch0 = u.pn * 64 + wc * 16 + (fq & 1) * 8 + (fq >> 1) * 4, chb = u.pn * 64 + wc * 16 + (fq & 1) * 8, up = fq >> 1;
;             f32x4 w[3];
; #pragma unroll
;             for (int k = 0; k < 3; ++k) w[k] = *(const f32x4*)(cwa + k * 1024 + ch0);
; template <bool ALIGN_EPI, class Epi, class Sched>
; DEV void gemm_phase(LAS unsigned char* lds, const Gemm g, const Sched& S, const Epi& E) {
;     ...
;     for (;;) {
;         const bool has_next = S.next(ui + 1, nxt);
;         const char* nA = has_next ? (const char*)g.A + (size_t)nxt.pm * tstep : cA; const char* nB = has_next ? (const char*)g.Bt + (size_t)nxt.pn * tstep : cB;
.LBB0_314:
	s_min_u32 s46, s8, 15
	v_and_b32_e32 v3, 15, v213
	v_min_u32_e32 v3, 11, v3
	v_lshrrev_b32_e32 v4, 2, v3
	v_and_b32_e32 v3, 3, v3
	v_lshl_add_u32 v4, v4, 10, v3
	s_lshl_b32 s46, s46, 6
	v_or_b32_e32 v3, v198, v200
	v_add3_u32 v4, v4, v3, s46
	v_lshlrev_b32_e32 v4, 2, v4
	global_load_dword v252, v4, s[52:53]
	s_ashr_i32 s93, s92, 31
	s_lshl_b64 s[46:47], s[92:93], 19
	s_add_u32 s88, s34, s46
	s_addc_u32 s89, s35, s47
	s_and_b64 s[46:47], s[44:45], exec
	s_cselect_b32 s17, s89, s5
	s_cselect_b32 s36, s88, s4
	s_ashr_i32 s85, s84, 31
	s_lshl_b64 s[46:47], s[84:85], 19
	s_add_u32 s90, s62, s46
	s_addc_u32 s91, s63, s47
	s_and_b64 s[46:47], s[44:45], exec
	s_cselect_b32 s41, s91, s7
	s_cselect_b32 s64, s90, s6
	s_add_u32 s70, s6, 0x100
	v_mov_b32_e32 v2, 0
	s_addc_u32 s85, s7, 0
	s_mov_b32 s87, -2
	v_mov_b32_e32 v3, v2
	v_mov_b64_e32 v[4:5], 0
	v_mov_b64_e32 v[6:7], 0
	v_mov_b64_e32 v[8:9], 0
	v_mov_b64_e32 v[18:19], 0
	v_mov_b64_e32 v[20:21], 0
	v_mov_b64_e32 v[22:23], 0
	v_mov_b64_e32 v[24:25], 0
	v_mov_b64_e32 v[34:35], 0
	v_mov_b64_e32 v[36:37], 0
	v_mov_b64_e32 v[38:39], 0
	v_mov_b64_e32 v[40:41], 0
	v_mov_b64_e32 v[50:51], 0
	v_mov_b64_e32 v[52:53], 0
	v_mov_b64_e32 v[54:55], 0
	v_mov_b64_e32 v[56:57], 0
	v_mov_b64_e32 v[10:11], 0
	v_mov_b64_e32 v[12:13], 0
	v_mov_b64_e32 v[14:15], 0
	v_mov_b64_e32 v[16:17], 0
	v_mov_b64_e32 v[26:27], 0
	v_mov_b64_e32 v[28:29], 0
	v_mov_b64_e32 v[30:31], 0
	v_mov_b64_e32 v[32:33], 0
	v_mov_b64_e32 v[42:43], 0
	v_mov_b64_e32 v[44:45], 0
	v_mov_b64_e32 v[46:47], 0
	v_mov_b64_e32 v[48:49], 0
	v_mov_b64_e32 v[58:59], 0
	v_mov_b64_e32 v[60:61], 0
	v_mov_b64_e32 v[62:63], 0
	v_mov_b64_e32 v[64:65], 0
	v_mov_b64_e32 v[66:67], 0
	v_mov_b64_e32 v[68:69], 0
	v_mov_b64_e32 v[70:71], 0
	v_mov_b64_e32 v[72:73], 0
	v_mov_b64_e32 v[82:83], 0
	v_mov_b64_e32 v[84:85], 0
	v_mov_b64_e32 v[86:87], 0
	v_mov_b64_e32 v[88:89], 0
	v_mov_b64_e32 v[98:99], 0
	v_mov_b64_e32 v[100:101], 0
	v_mov_b64_e32 v[102:103], 0
	v_mov_b64_e32 v[104:105], 0
	v_mov_b64_e32 v[114:115], 0
	v_mov_b64_e32 v[116:117], 0
	v_mov_b64_e32 v[118:119], 0
	v_mov_b64_e32 v[120:121], 0
	v_mov_b64_e32 v[74:75], 0
	v_mov_b64_e32 v[76:77], 0
	v_mov_b64_e32 v[78:79], 0
	v_mov_b64_e32 v[80:81], 0
	v_mov_b64_e32 v[90:91], 0
	v_mov_b64_e32 v[92:93], 0
	v_mov_b64_e32 v[94:95], 0
	v_mov_b64_e32 v[96:97], 0
	v_mov_b64_e32 v[106:107], 0
	v_mov_b64_e32 v[108:109], 0
	v_mov_b64_e32 v[110:111], 0
	v_mov_b64_e32 v[112:113], 0
	v_mov_b64_e32 v[122:123], 0
	v_mov_b64_e32 v[124:125], 0
	v_mov_b64_e32 v[126:127], 0
	v_mov_b64_e32 v[128:129], 0

; #define LAS __attribute__((address_space(3)))
;     DEV bool operator()(f32x4 (&acc)[2][2][4][2], const Unit& u, int wr, int wc, int fr, int fq) const {
;     ...
;         if (!act_mode && u.pn < 16) {
;             const int ch0 = u.pn * 64 + wc * 16 + (fq & 1) * 8 + (fq >> 1) * 4, chb = u.pn * 64 + wc * 16 + (fq & 1) * 8, up = fq >> 1;
;             f32x4 w[3];
; #pragma unroll
;             for (int k = 0; k < 3; ++k) w[k] = *(const f32x4*)(cwa + k * 1024 + ch0);
;             f32x4 xp[8];
; #pragma unroll
;             for (int i = 0; i < 8; ++i) xp[i] = acc[i >> 2][0][i & 3][1] * acc[i >> 2][1][i & 3][0];
;             f32x4 p6, p7;
; #pragma unroll
;             for (int c = 0; c < 4; ++c) { p6[c] = __shfl_up(xp[6][c], 1); p7[c] = __shfl_up(xp[7][c], 1); }
;             LAS f32x4* EX = (LAS f32x4*)ex + (wc * 4 + fq) * 2;
;             if (wr == 0 && fr == 15) { EX[0] = xp[6]; EX[1] = xp[7]; }
.LBB0_436:
	s_and_b64 vcc, exec, s[4:5]
	s_cbranch_vccz .LBB0_448
	v_lshl_or_b32 v196, s8, 6, v198
	v_or_b32_e32 v166, v196, v200
	v_ashrrev_i32_e32 v167, 31, v166
	v_add_u32_e32 v0, -1, v213
	v_and_b32_e32 v150, 64, v213
	v_mov_b32_dpp v130, v252 row_newbcast:0 row_mask:0xf bank_mask:0xf
	v_mov_b32_dpp v131, v252 row_newbcast:1 row_mask:0xf bank_mask:0xf
	v_mov_b32_dpp v132, v252 row_newbcast:2 row_mask:0xf bank_mask:0xf
	v_mov_b32_dpp v133, v252 row_newbcast:3 row_mask:0xf bank_mask:0xf
	v_mov_b32_dpp v134, v252 row_newbcast:4 row_mask:0xf bank_mask:0xf
	v_mov_b32_dpp v135, v252 row_newbcast:5 row_mask:0xf bank_mask:0xf
	v_mov_b32_dpp v136, v252 row_newbcast:6 row_mask:0xf bank_mask:0xf
	v_mov_b32_dpp v137, v252 row_newbcast:7 row_mask:0xf bank_mask:0xf
	v_mov_b32_dpp v138, v252 row_newbcast:8 row_mask:0xf bank_mask:0xf
	v_mov_b32_dpp v139, v252 row_newbcast:9 row_mask:0xf bank_mask:0xf
	v_mov_b32_dpp v140, v252 row_newbcast:10 row_mask:0xf bank_mask:0xf
	v_mov_b32_dpp v141, v252 row_newbcast:11 row_mask:0xf bank_mask:0xf
	v_cmp_lt_i32_e32 vcc, v0, v150
	v_pk_mul_f32 v[144:145], v[28:29], v[24:25]
	v_pk_mul_f32 v[142:143], v[26:27], v[22:23]
	v_cndmask_b32_e32 v0, v0, v213, vcc
	v_pk_mul_f32 v[148:149], v[12:13], v[8:9]
	v_pk_mul_f32 v[146:147], v[10:11], v[6:7]
	v_lshlrev_b32_e32 v0, 2, v0
	ds_bpermute_b32 v162, v0, v142
	ds_bpermute_b32 v158, v0, v146
	ds_bpermute_b32 v163, v0, v143
	ds_bpermute_b32 v159, v0, v147
	ds_bpermute_b32 v164, v0, v144
	ds_bpermute_b32 v160, v0, v148
	ds_bpermute_b32 v165, v0, v145
	ds_bpermute_b32 v161, v0, v149
	s_mov_b64 s[4:5], exec
	v_readlane_b32 s6, v255, 4
	v_readlane_b32 s7, v255, 5
	s_and_b64 s[6:7], s[4:5], s[6:7]
	s_mov_b64 exec, s[6:7]
	s_cbranch_execz .LBB0_439
	ds_write_b128 v204, v[142:145]
	ds_write_b128 v204, v[146:149] offset:16

; DEV unsigned cvt_pk_bf16(float lo, float hi) { unsigned r; asm volatile("v_cvt_pk_bf16_f32 %0, %1, %2" : "=v"(r) : "v"(lo), "v"(hi)); return r; }
;     DEV bool operator()(f32x4 (&acc)[2][2][4][2], const Unit& u, int wr, int wc, int fr, int fq) const {
;     ...
; #pragma unroll
;             for (int ip = 0; ip < 4; ++ip) { u32x2 o[2], q2[2];
; #pragma unroll
;                 for (int ii = 0; ii < 2; ++ii) { const int i = ip * 2 + ii;
;                     const f32x4 xm1 = i >= 1 ? xp[i >= 1 ? i - 1 : 0] : p7, xm2 = i >= 2 ? xp[i >= 2 ? i - 2 : 0] : (i == 0 ? p6 : p7);
;                     const f32x4 y = acc[i >> 2][0][i & 3][0] * (w[0] * xm2 + w[1] * xm1 + w[2] * xp[i]);
;                     o[ii].x = cvt_pk_bf16(y[0], y[1]); o[ii].y = cvt_pk_bf16(y[2], y[3]);
;                     const f32x4 qv = acc[i >> 2][1][i & 3][1];
;                     q2[ii].x = cvt_pk_bf16(qv[0], qv[1]); q2[ii].y = cvt_pk_bf16(qv[2], qv[3]); }
;                 const size_t tok = (size_t)(row0 + ip * 2 + up);
;                 const u32x4 ow = pair32(o[0], o[1]), qw = pair32(q2[0], q2[1]);
;                 if (!(halo && ip == 0)) *(u32x4*)(OA + tok * 1024 + chb) = ow;
;                 *(u32x4*)(QB + tok * 1024 + chb) = qw; }
.LBB0_445:
	s_or_b64 exec, exec, s[4:5]
	s_waitcnt lgkmcnt(0)
	v_pk_mul_f32 v[164:165], v[132:133], v[164:165]
	v_pk_mul_f32 v[162:163], v[130:131], v[162:163]
	v_pk_fma_f32 v[164:165], v[136:137], v[160:161], v[164:165]
	v_pk_fma_f32 v[162:163], v[134:135], v[158:159], v[162:163]
	v_pk_mul_f32 v[160:161], v[132:133], v[160:161]
	v_pk_mul_f32 v[158:159], v[130:131], v[158:159]
	v_pk_fma_f32 v[164:165], v[156:157], v[140:141], v[164:165]
	v_pk_fma_f32 v[162:163], v[154:155], v[138:139], v[162:163]
	v_pk_fma_f32 v[160:161], v[156:157], v[136:137], v[160:161]
	v_pk_fma_f32 v[158:159], v[154:155], v[134:135], v[158:159]
	v_or_b32_e32 v194, v205, v199
	v_pk_mul_f32 v[164:165], v[128:129], v[164:165]
	v_pk_mul_f32 v[162:163], v[126:127], v[162:163]
	v_pk_fma_f32 v[160:161], v[152:153], v[140:141], v[160:161]
	v_pk_fma_f32 v[158:159], v[150:151], v[138:139], v[158:159]
	v_cvt_pk_bf16_f32 v166, v162, v163
	v_cvt_pk_bf16_f32 v167, v164, v165
	v_cvt_pk_bf16_f32 v162, v114, v115
	v_cvt_pk_bf16_f32 v163, v116, v117
	v_pk_mul_f32 v[160:161], v[112:113], v[160:161]
	v_pk_mul_f32 v[158:159], v[110:111], v[158:159]
	v_ashrrev_i32_e32 v195, 31, v194
	v_cvt_pk_bf16_f32 v168, v158, v159
	v_cvt_pk_bf16_f32 v169, v160, v161
	v_cvt_pk_bf16_f32 v164, v98, v99
	v_cvt_pk_bf16_f32 v165, v100, v101
	v_ashrrev_i32_e32 v197, 31, v196
	v_permlane32_swap_b32_e32 v166, v168
	v_permlane32_swap_b32_e32 v167, v169
	v_permlane32_swap_b32_e32 v162, v164
	v_permlane32_swap_b32_e32 v163, v165
	v_lshlrev_b64 v[158:159], 11, v[194:195]
	s_and_saveexec_b64 s[4:5], s[42:43]
	s_cbranch_execz .LBB0_447
	v_lshl_add_u64 v[160:161], s[22:23], 0, v[158:159]
	v_lshl_add_u64 v[160:161], v[196:197], 1, v[160:161]
	global_store_dwordx4 v[160:161], v[166:169], off
